# remaining six register-renamed E1/E2/E3 all-reduce butterflies converted in place to DPP + permlane swaps, on top of v066
# speedup vs baseline: 1.0075x; 1.0075x over previous
; __device__ __forceinline__ unsigned pk2(float lo, float hi) { const f32x2_pk v = {lo, hi}; return __builtin_bit_cast(unsigned, __builtin_convertvector(v, bf16x2_pk)); }
; __device__ __forceinline__ float bflo(unsigned w) { return __uint_as_float(w << 16); }
; __device__ __forceinline__ float bfhi(unsigned w) { return __uint_as_float(w & 0xffff0000u); }
; #define RS ((float*)(WSP() + WS_RS))
; template <bool HAS_G, bool HAS_PRE, bool HAS_F, bool HAS_P, bool HIN32, bool HOUT32> ...
;     ...
;         for (int j = 0; j < 4; ++j) { if (HIN32) v[j] = h32[u][j]; else v[j] = (f32x4){bflo(hbr[u][j].x), bfhi(hbr[u][j].x), bflo(hbr[u][j].y), bfhi(hbr[u][j].y)};
;             if (HAS_G) g[j] = (f32x4){bflo(gbr[u][j].x), bfhi(gbr[u][j].x), bflo(gbr[u][j].y), bfhi(gbr[u][j].y)}; }
;         if (m + 2 * NGW < M) E_LOAD(u, m + 2 * NGW);
;         if (HAS_G) {
;             float ss = 0.f;
; #pragma unroll
;             for (int j = 0; j < 4; ++j) ss += (g[j][0] * g[j][0] + g[j][1] * g[j][1]) + (g[j][2] * g[j][2] + g[j][3] * g[j][3]);
;             const float r = __builtin_amdgcn_rsqf(wave_sum(ss) * (1.f / DM) + EPS)    ;
; #pragma unroll
;             for (int j = 0; j < 4; ++j) { v[j] = v[j] + g[j] * r * gp[j];
;                 if (HOUT32) __builtin_nontemporal_store(v[j], (f32x4*)((float*)hout_ + mm * DM + 4 * lane + 256 * j));
;                 else { v2u w; w.x = pk2(v[j][0], v[j][1]); w.y = pk2(v[j][2], v[j][3]); *(v2u*)((bf16*)hout_ + mm * DM + 4 * lane + 256 * j) = w; } }
;         }
;         if (!HAS_G && hout_) {
; #pragma unroll
;             for (int j = 0; j < 4; ++j) { v2u w; w.x = pk2(v[j][0], v[j][1]); w.y = pk2(v[j][2], v[j][3]); *(v2u*)((bf16*)hout_ + mm * DM + 4 * lane + 256 * j) = w; } }
;         if (HAS_PRE) {
;             float ss = 0.f;
; #pragma unroll
;             for (int j = 0; j < 4; ++j) ss += (v[j][0] * v[j][0] + v[j][1] * v[j][1]) + (v[j][2] * v[j][2] + v[j][3] * v[j][3]);
;             const float r = __builtin_amdgcn_rsqf(wave_sum(ss) * (1.f / DM) + EPS)    ;
;             if (lane == 0) RS[mm] = r;
.LBB0_604:
	v_lshlrev_b32_e32 v79, 16, v71
	v_lshlrev_b32_e32 v78, 16, v70
	v_and_b32_e32 v71, 0xffff0000, v71
	v_and_b32_e32 v70, 0xffff0000, v70
	v_pk_mul_f32 v[86:87], v[70:71], v[70:71]
	v_lshlrev_b32_e32 v81, 16, v67
	v_lshlrev_b32_e32 v80, 16, v66
	v_and_b32_e32 v67, 0xffff0000, v67
	v_and_b32_e32 v66, 0xffff0000, v66
	v_pk_fma_f32 v[86:87], v[78:79], v[78:79], v[86:87]
	v_lshlrev_b32_e32 v82, 16, v64
	v_and_b32_e32 v83, 0xffff0000, v64
	v_lshlrev_b32_e32 v64, 16, v65
	v_lshlrev_b32_e32 v84, 16, v60
	v_pk_add_f32 v[86:87], v[86:87], v[86:87] op_sel_hi:[0,1]
	v_pk_mul_f32 v[88:89], v[66:67], v[66:67]
	v_and_b32_e32 v65, 0xffff0000, v65
	v_pk_fma_f32 v[88:89], v[80:81], v[80:81], v[88:89]
	v_mul_f32_e32 v85, v82, v82
	v_mul_f32_e32 v91, v83, v83
	v_mul_f32_e32 v86, v64, v64
	v_mov_b32_e32 v90, v84
	v_and_b32_e32 v98, 0xffff0000, v60
	v_lshlrev_b32_e32 v60, 16, v61
	v_and_b32_e32 v61, 0xffff0000, v61
	v_pk_add_f32 v[88:89], v[88:89], v[88:89] op_sel_hi:[0,1]
	v_pk_fma_f32 v[92:93], v[64:65], v[64:65], v[86:87] op_sel_hi:[1,1,0]
	v_pk_add_f32 v[90:91], v[84:85], v[90:91]
	v_mul_f32_e32 v92, v98, v98
	v_mul_f32_e32 v88, v60, v60
	v_mul_f32_e32 v86, v61, v61
	v_mul_f32_e32 v94, v84, v84
	v_mov_b32_e32 v95, v91
	v_pk_add_f32 v[90:91], v[94:95], v[92:93]
	v_pk_add_f32 v[86:87], v[88:89], v[86:87]
	v_mov_b32_e32 v96, v78
	v_pk_add_f32 v[86:87], v[90:91], v[86:87]
	v_mov_b32_e32 v97, v70
	v_add_f32_e32 v85, v86, v87
	v_mov_b32_e32 v70, v79
	v_and_b32_e32 v87, 0xffff0000, v68
	v_and_b32_e32 v93, 0xffff0000, v56
	v_mov_b32_e32 v78, v80
	v_mov_b32_e32 v79, v66
	v_mov_b32_e32 v66, v81
	v_and_b32_e32 v89, 0xffff0000, v62
	v_and_b32_e32 v91, 0xffff0000, v58
	v_lshlrev_b32_e32 v86, 16, v68
	v_lshlrev_b32_e32 v68, 16, v69
	v_and_b32_e32 v69, 0xffff0000, v69
	s_mov_b32 s7, 0x6800000
	v_lshlrev_b32_e32 v88, 16, v62
	v_lshlrev_b32_e32 v62, 16, v63
	v_and_b32_e32 v63, 0xffff0000, v63
	v_lshlrev_b32_e32 v90, 16, v58
	v_lshlrev_b32_e32 v58, 16, v59
	v_and_b32_e32 v59, 0xffff0000, v59
	v_lshlrev_b32_e32 v92, 16, v56
	v_lshlrev_b32_e32 v56, 16, v57
	v_and_b32_e32 v57, 0xffff0000, v57
	s_waitcnt lgkmcnt(0)
	s_nop 1
	v_add_f32_dpp v85, v85, v85 quad_perm:[1,0,3,2] row_mask:0xf bank_mask:0xf
	s_nop 1
	v_add_f32_dpp v85, v85, v85 quad_perm:[2,3,0,1] row_mask:0xf bank_mask:0xf
	s_nop 1
	v_add_f32_dpp v85, v85, v85 row_half_mirror row_mask:0xf bank_mask:0xf
	s_nop 1
	v_add_f32_dpp v85, v85, v85 row_mirror row_mask:0xf bank_mask:0xf
	v_mov_b32_e32 v94, v85
	s_nop 1
	v_permlane16_swap_b32_e32 v85, v94
	v_add_f32_e32 v85, v85, v94
	v_mov_b32_e32 v94, v85
	s_nop 1
	v_permlane32_swap_b32_e32 v85, v94
	v_add_f32_e32 v85, v85, v94
	v_fmamk_f32 v85, v85, 0x3a800000, v214
	v_rsq_f32_e32 v94, v85
	v_mov_b32_e32 v85, v98
	v_pk_mul_f32 v[96:97], v[94:95], v[96:97] op_sel_hi:[0,1]
	v_pk_mul_f32 v[70:71], v[94:95], v[70:71] op_sel_hi:[0,1]
	v_pk_fma_f32 v[68:69], v[4:5], v[70:71], v[68:69]
	v_pk_fma_f32 v[70:71], v[2:3], v[96:97], v[86:87]
	v_pk_mul_f32 v[60:61], v[60:61], v[94:95] op_sel_hi:[1,0]
	v_pk_mul_f32 v[78:79], v[94:95], v[78:79] op_sel_hi:[0,1]
	v_pk_mul_f32 v[66:67], v[94:95], v[66:67] op_sel_hi:[0,1]
	v_pk_fma_f32 v[60:61], v[16:17], v[60:61], v[56:57]
	v_mul_f32_e32 v56, v71, v71
	v_mul_f32_e32 v57, v69, v69
	v_pk_fma_f32 v[62:63], v[8:9], v[66:67], v[62:63]
	v_pk_fma_f32 v[66:67], v[6:7], v[78:79], v[88:89]
	v_fmac_f32_e32 v56, v70, v70
	v_fmac_f32_e32 v57, v68, v68
	v_add_f32_e32 v56, v56, v57
	v_mul_f32_e32 v57, v67, v67
	v_mul_f32_e32 v80, v63, v63
	v_pk_mul_f32 v[78:79], v[82:83], v[94:95] op_sel_hi:[1,0]
	v_pk_mul_f32 v[64:65], v[64:65], v[94:95] op_sel_hi:[1,0]
	v_fmac_f32_e32 v57, v66, v66
	v_fmac_f32_e32 v80, v62, v62
	v_pk_fma_f32 v[58:59], v[12:13], v[64:65], v[58:59]
	v_pk_fma_f32 v[64:65], v[10:11], v[78:79], v[90:91]
	v_add_f32_e32 v57, v57, v80
	v_add_f32_e32 v56, v56, v57
	v_mul_f32_e32 v57, v65, v65
	v_mul_f32_e32 v80, v59, v59
	v_pk_mul_f32 v[78:79], v[84:85], v[94:95] op_sel_hi:[1,0]
	v_fmac_f32_e32 v57, v64, v64
	v_fmac_f32_e32 v80, v58, v58
	v_pk_fma_f32 v[78:79], v[14:15], v[78:79], v[92:93]
	v_add_f32_e32 v57, v57, v80
	v_add_f32_e32 v56, v57, v56
	v_mul_f32_e32 v57, v79, v79
	v_mul_f32_e32 v80, v61, v61
	v_fmac_f32_e32 v57, v78, v78
	v_fmac_f32_e32 v80, v60, v60
	v_add_f32_e32 v57, v57, v80
	v_add_f32_e32 v56, v57, v56
	s_waitcnt lgkmcnt(0)
	s_nop 1
	v_add_f32_dpp v56, v56, v56 quad_perm:[1,0,3,2] row_mask:0xf bank_mask:0xf
	s_nop 1
	v_add_f32_dpp v56, v56, v56 quad_perm:[2,3,0,1] row_mask:0xf bank_mask:0xf
	s_nop 1
	v_add_f32_dpp v56, v56, v56 row_half_mirror row_mask:0xf bank_mask:0xf
	s_nop 1
	v_add_f32_dpp v56, v56, v56 row_mirror row_mask:0xf bank_mask:0xf
	v_mov_b32_e32 v57, v56
	s_nop 1
	v_permlane16_swap_b32_e32 v56, v57
	v_add_f32_e32 v56, v56, v57
	v_mov_b32_e32 v57, v56
	s_nop 1
	v_permlane32_swap_b32_e32 v56, v57
	v_add_f32_e32 v56, v56, v57
	v_cvt_pk_bf16_f32 v70, v70, v71
	v_cvt_pk_bf16_f32 v71, v68, v69
	v_mov_b32_e32 v80, v56
	v_lshl_add_u64 v[56:57], s[18:19], 0, v[0:1]
	v_add_co_u32_e32 v68, vcc, s7, v56
	v_cvt_pk_bf16_f32 v56, v66, v67
	v_addc_co_u32_e32 v69, vcc, 0, v57, vcc
	v_cvt_pk_bf16_f32 v57, v62, v63
	global_store_dwordx2 v[68:69], v[56:57], off offset:512
	v_mov_b32_e32 v66, v80
	v_cvt_pk_bf16_f32 v62, v64, v65
	v_cvt_pk_bf16_f32 v63, v58, v59
	v_cvt_pk_bf16_f32 v58, v78, v79
	v_cvt_pk_bf16_f32 v59, v60, v61
	v_mov_b32_e32 v56, v66
	global_store_dwordx2 v[68:69], v[70:71], off
	global_store_dwordx2 v[68:69], v[62:63], off offset:1024
	global_store_dwordx2 v[68:69], v[58:59], off offset:1536
	s_and_saveexec_b64 s[20:21], s[4:5]
	s_cbranch_execz .LBB0_606
	v_fmamk_f32 v56, v56, 0x3a800000, v214
	v_rsq_f32_e32 v56, v56
	global_store_dword v1, v56, s[14:15]

; __device__ __forceinline__ unsigned pk2(float lo, float hi) { const f32x2_pk v = {lo, hi}; return __builtin_bit_cast(unsigned, __builtin_convertvector(v, bf16x2_pk)); }
; __device__ __forceinline__ float bflo(unsigned w) { return __uint_as_float(w << 16); }
; __device__ __forceinline__ float bfhi(unsigned w) { return __uint_as_float(w & 0xffff0000u); }
; #define RS ((float*)(WSP() + WS_RS))
; template <bool HAS_G, bool HAS_PRE, bool HAS_F, bool HAS_P, bool HIN32, bool HOUT32> ...
;     ...
;         for (int j = 0; j < 4; ++j) { if (HIN32) v[j] = h32[u][j]; else v[j] = (f32x4){bflo(hbr[u][j].x), bfhi(hbr[u][j].x), bflo(hbr[u][j].y), bfhi(hbr[u][j].y)};
;             if (HAS_G) g[j] = (f32x4){bflo(gbr[u][j].x), bfhi(gbr[u][j].x), bflo(gbr[u][j].y), bfhi(gbr[u][j].y)}; }
;         if (m + 2 * NGW < M) E_LOAD(u, m + 2 * NGW);
;         if (HAS_G) {
;             float ss = 0.f;
; #pragma unroll
;             for (int j = 0; j < 4; ++j) ss += (g[j][0] * g[j][0] + g[j][1] * g[j][1]) + (g[j][2] * g[j][2] + g[j][3] * g[j][3]);
;             const float r = __builtin_amdgcn_rsqf(wave_sum(ss) * (1.f / DM) + EPS)    ;
; #pragma unroll
;             for (int j = 0; j < 4; ++j) { v[j] = v[j] + g[j] * r * gp[j];
;                 if (HOUT32) __builtin_nontemporal_store(v[j], (f32x4*)((float*)hout_ + mm * DM + 4 * lane + 256 * j));
;                 else { v2u w; w.x = pk2(v[j][0], v[j][1]); w.y = pk2(v[j][2], v[j][3]); *(v2u*)((bf16*)hout_ + mm * DM + 4 * lane + 256 * j) = w; } }
;         }
;         if (!HAS_G && hout_) {
; #pragma unroll
;             for (int j = 0; j < 4; ++j) { v2u w; w.x = pk2(v[j][0], v[j][1]); w.y = pk2(v[j][2], v[j][3]); *(v2u*)((bf16*)hout_ + mm * DM + 4 * lane + 256 * j) = w; } }
;         if (HAS_PRE) {
;             float ss = 0.f;
; #pragma unroll
;             for (int j = 0; j < 4; ++j) ss += (v[j][0] * v[j][0] + v[j][1] * v[j][1]) + (v[j][2] * v[j][2] + v[j][3] * v[j][3]);
;             const float r = __builtin_amdgcn_rsqf(wave_sum(ss) * (1.f / DM) + EPS)    ;
;             if (lane == 0) RS[mm] = r;
.LBB0_608:
	v_lshlrev_b32_e32 v79, 16, v55
	v_lshlrev_b32_e32 v78, 16, v54
	v_and_b32_e32 v55, 0xffff0000, v55
	v_and_b32_e32 v54, 0xffff0000, v54
	v_pk_mul_f32 v[86:87], v[54:55], v[54:55]
	v_lshlrev_b32_e32 v81, 16, v53
	v_lshlrev_b32_e32 v80, 16, v52
	v_and_b32_e32 v53, 0xffff0000, v53
	v_and_b32_e32 v52, 0xffff0000, v52
	v_pk_fma_f32 v[86:87], v[78:79], v[78:79], v[86:87]
	v_lshlrev_b32_e32 v82, 16, v50
	v_and_b32_e32 v83, 0xffff0000, v50
	v_lshlrev_b32_e32 v50, 16, v51
	v_lshlrev_b32_e32 v84, 16, v48
	v_pk_add_f32 v[86:87], v[86:87], v[86:87] op_sel_hi:[0,1]
	v_pk_mul_f32 v[88:89], v[52:53], v[52:53]
	v_and_b32_e32 v51, 0xffff0000, v51
	v_pk_fma_f32 v[88:89], v[80:81], v[80:81], v[88:89]
	v_mul_f32_e32 v85, v82, v82
	v_mul_f32_e32 v91, v83, v83
	v_mul_f32_e32 v86, v50, v50
	v_mov_b32_e32 v90, v84
	v_and_b32_e32 v98, 0xffff0000, v48
	v_lshlrev_b32_e32 v48, 16, v49
	v_and_b32_e32 v49, 0xffff0000, v49
	v_pk_add_f32 v[88:89], v[88:89], v[88:89] op_sel_hi:[0,1]
	v_pk_fma_f32 v[92:93], v[50:51], v[50:51], v[86:87] op_sel_hi:[1,1,0]
	v_pk_add_f32 v[90:91], v[84:85], v[90:91]
	v_mul_f32_e32 v92, v98, v98
	v_mul_f32_e32 v88, v48, v48
	v_mul_f32_e32 v86, v49, v49
	v_mul_f32_e32 v94, v84, v84
	v_mov_b32_e32 v95, v91
	v_pk_add_f32 v[90:91], v[94:95], v[92:93]
	v_pk_add_f32 v[86:87], v[88:89], v[86:87]
	v_mov_b32_e32 v96, v78
	v_pk_add_f32 v[86:87], v[90:91], v[86:87]
	v_mov_b32_e32 v97, v54
	v_add_f32_e32 v85, v86, v87
	v_mov_b32_e32 v54, v79
	v_and_b32_e32 v87, 0xffff0000, v46
	v_and_b32_e32 v93, 0xffff0000, v40
	v_mov_b32_e32 v78, v80
	v_mov_b32_e32 v79, v52
	v_mov_b32_e32 v52, v81
	v_and_b32_e32 v89, 0xffff0000, v44
	v_and_b32_e32 v91, 0xffff0000, v42
	v_lshlrev_b32_e32 v86, 16, v46
	v_lshlrev_b32_e32 v46, 16, v47
	v_and_b32_e32 v47, 0xffff0000, v47
	s_add_i32 s20, s28, s2
	v_lshlrev_b32_e32 v88, 16, v44
	v_lshlrev_b32_e32 v44, 16, v45
	v_and_b32_e32 v45, 0xffff0000, v45
	s_ashr_i32 s21, s20, 31
	v_lshlrev_b32_e32 v90, 16, v42
	v_lshlrev_b32_e32 v42, 16, v43
	v_and_b32_e32 v43, 0xffff0000, v43
	s_lshl_b64 s[22:23], s[20:21], 11
	v_lshlrev_b32_e32 v92, 16, v40
	v_lshlrev_b32_e32 v40, 16, v41
	v_and_b32_e32 v41, 0xffff0000, v41
	s_waitcnt lgkmcnt(0)
	s_nop 1
	v_add_f32_dpp v85, v85, v85 quad_perm:[1,0,3,2] row_mask:0xf bank_mask:0xf
	s_nop 1
	v_add_f32_dpp v85, v85, v85 quad_perm:[2,3,0,1] row_mask:0xf bank_mask:0xf
	s_nop 1
	v_add_f32_dpp v85, v85, v85 row_half_mirror row_mask:0xf bank_mask:0xf
	s_nop 1
	v_add_f32_dpp v85, v85, v85 row_mirror row_mask:0xf bank_mask:0xf
	v_mov_b32_e32 v94, v85
	s_nop 1
	v_permlane16_swap_b32_e32 v85, v94
	v_add_f32_e32 v85, v85, v94
	v_mov_b32_e32 v94, v85
	s_nop 1
	v_permlane32_swap_b32_e32 v85, v94
	v_add_f32_e32 v85, v85, v94
	v_fmamk_f32 v85, v85, 0x3a800000, v214
	v_rsq_f32_e32 v94, v85
	v_mov_b32_e32 v85, v98
	v_pk_mul_f32 v[96:97], v[94:95], v[96:97] op_sel_hi:[0,1]
	v_pk_mul_f32 v[54:55], v[94:95], v[54:55] op_sel_hi:[0,1]
	v_pk_fma_f32 v[46:47], v[4:5], v[54:55], v[46:47]
	v_pk_fma_f32 v[54:55], v[2:3], v[96:97], v[86:87]
	v_pk_mul_f32 v[48:49], v[48:49], v[94:95] op_sel_hi:[1,0]
	v_pk_mul_f32 v[78:79], v[94:95], v[78:79] op_sel_hi:[0,1]
	v_pk_mul_f32 v[52:53], v[94:95], v[52:53] op_sel_hi:[0,1]
	v_pk_fma_f32 v[48:49], v[16:17], v[48:49], v[40:41]
	v_mul_f32_e32 v40, v55, v55
	v_mul_f32_e32 v41, v47, v47
	v_pk_fma_f32 v[44:45], v[8:9], v[52:53], v[44:45]
	v_pk_fma_f32 v[52:53], v[6:7], v[78:79], v[88:89]
	v_fmac_f32_e32 v40, v54, v54
	v_fmac_f32_e32 v41, v46, v46
	v_add_f32_e32 v40, v40, v41
	v_mul_f32_e32 v41, v53, v53
	v_mul_f32_e32 v80, v45, v45
	v_pk_mul_f32 v[78:79], v[82:83], v[94:95] op_sel_hi:[1,0]
	v_pk_mul_f32 v[50:51], v[50:51], v[94:95] op_sel_hi:[1,0]
	v_fmac_f32_e32 v41, v52, v52
	v_fmac_f32_e32 v80, v44, v44
	v_pk_fma_f32 v[42:43], v[12:13], v[50:51], v[42:43]
	v_pk_fma_f32 v[50:51], v[10:11], v[78:79], v[90:91]
	v_add_f32_e32 v41, v41, v80
	v_add_f32_e32 v40, v40, v41
	v_mul_f32_e32 v41, v51, v51
	v_mul_f32_e32 v80, v43, v43
	v_pk_mul_f32 v[78:79], v[84:85], v[94:95] op_sel_hi:[1,0]
	v_fmac_f32_e32 v41, v50, v50
	v_fmac_f32_e32 v80, v42, v42
	v_pk_fma_f32 v[78:79], v[14:15], v[78:79], v[92:93]
	v_add_f32_e32 v41, v41, v80
	v_add_f32_e32 v40, v41, v40
	v_mul_f32_e32 v41, v79, v79
	v_mul_f32_e32 v80, v49, v49
	v_fmac_f32_e32 v41, v78, v78
	v_fmac_f32_e32 v80, v48, v48
	v_add_f32_e32 v41, v41, v80
	v_add_f32_e32 v40, v41, v40
	s_waitcnt lgkmcnt(0)
	s_nop 1
	v_add_f32_dpp v40, v40, v40 quad_perm:[1,0,3,2] row_mask:0xf bank_mask:0xf
	s_nop 1
	v_add_f32_dpp v40, v40, v40 quad_perm:[2,3,0,1] row_mask:0xf bank_mask:0xf
	s_nop 1
	v_add_f32_dpp v40, v40, v40 row_half_mirror row_mask:0xf bank_mask:0xf
	s_nop 1
	v_add_f32_dpp v40, v40, v40 row_mirror row_mask:0xf bank_mask:0xf
	v_mov_b32_e32 v41, v40
	s_nop 1
	v_permlane16_swap_b32_e32 v40, v41
	v_add_f32_e32 v40, v40, v41
	v_mov_b32_e32 v41, v40
	s_nop 1
	v_permlane32_swap_b32_e32 v40, v41
	v_add_f32_e32 v40, v40, v41
	v_lshl_add_u64 v[80:81], v[18:19], 0, s[22:23]
	v_mov_b32_e32 v82, v40
	v_cvt_pk_bf16_f32 v41, v46, v47
	v_cvt_pk_bf16_f32 v40, v54, v55
	global_store_dwordx2 v[80:81], v[40:41], off
	v_cvt_pk_bf16_f32 v40, v52, v53
	v_mov_b32_e32 v46, v82
	v_cvt_pk_bf16_f32 v41, v44, v45
	global_store_dwordx2 v[80:81], v[40:41], off offset:512
	v_cvt_pk_bf16_f32 v44, v50, v51
	v_cvt_pk_bf16_f32 v45, v42, v43
	v_mov_b32_e32 v40, v46
	v_cvt_pk_bf16_f32 v42, v78, v79
	v_cvt_pk_bf16_f32 v43, v48, v49
	global_store_dwordx2 v[80:81], v[44:45], off offset:1024
	global_store_dwordx2 v[80:81], v[42:43], off offset:1536
	s_and_saveexec_b64 s[22:23], s[4:5]
	s_cbranch_execz .LBB0_601
	v_fmamk_f32 v40, v40, 0x3a800000, v214
	v_rsq_f32_e32 v40, v40
	s_lshl_b64 s[20:21], s[20:21], 2
	s_add_u32 s20, s25, s20
	s_addc_u32 s21, s26, s21
	global_store_dword v1, v40, s[20:21]
	s_branch .LBB0_601

; __device__ __forceinline__ unsigned pk2(float lo, float hi) { const f32x2_pk v = {lo, hi}; return __builtin_bit_cast(unsigned, __builtin_convertvector(v, bf16x2_pk)); }
; __device__ __forceinline__ float bflo(unsigned w) { return __uint_as_float(w << 16); }
; __device__ __forceinline__ float bfhi(unsigned w) { return __uint_as_float(w & 0xffff0000u); }
; #define RS ((float*)(WSP() + WS_RS))
; template <bool HAS_G, bool HAS_PRE, bool HAS_F, bool HAS_P, bool HIN32, bool HOUT32> ...
;     ...
;         for (int j = 0; j < 4; ++j) { if (HIN32) v[j] = h32[u][j]; else v[j] = (f32x4){bflo(hbr[u][j].x), bfhi(hbr[u][j].x), bflo(hbr[u][j].y), bfhi(hbr[u][j].y)};
;             if (HAS_G) g[j] = (f32x4){bflo(gbr[u][j].x), bfhi(gbr[u][j].x), bflo(gbr[u][j].y), bfhi(gbr[u][j].y)}; }
;         if (m + 2 * NGW < M) E_LOAD(u, m + 2 * NGW);
;         if (HAS_G) {
;             float ss = 0.f;
; #pragma unroll
;             for (int j = 0; j < 4; ++j) ss += (g[j][0] * g[j][0] + g[j][1] * g[j][1]) + (g[j][2] * g[j][2] + g[j][3] * g[j][3]);
;             const float r = __builtin_amdgcn_rsqf(wave_sum(ss) * (1.f / DM) + EPS)    ;
; #pragma unroll
;             for (int j = 0; j < 4; ++j) { v[j] = v[j] + g[j] * r * gp[j];
;                 if (HOUT32) __builtin_nontemporal_store(v[j], (f32x4*)((float*)hout_ + mm * DM + 4 * lane + 256 * j));
;                 else { v2u w; w.x = pk2(v[j][0], v[j][1]); w.y = pk2(v[j][2], v[j][3]); *(v2u*)((bf16*)hout_ + mm * DM + 4 * lane + 256 * j) = w; } }
;         }
;         if (!HAS_G && hout_) {
; #pragma unroll
;             for (int j = 0; j < 4; ++j) { v2u w; w.x = pk2(v[j][0], v[j][1]); w.y = pk2(v[j][2], v[j][3]); *(v2u*)((bf16*)hout_ + mm * DM + 4 * lane + 256 * j) = w; } }
;         if (HAS_PRE) {
;             float ss = 0.f;
; #pragma unroll
;             for (int j = 0; j < 4; ++j) ss += (v[j][0] * v[j][0] + v[j][1] * v[j][1]) + (v[j][2] * v[j][2] + v[j][3] * v[j][3]);
;             const float r = __builtin_amdgcn_rsqf(wave_sum(ss) * (1.f / DM) + EPS)    ;
;             if (lane == 0) RS[mm] = r;
.LBB0_987:
	v_lshlrev_b32_e32 v167, 16, v157
	v_lshlrev_b32_e32 v166, 16, v156
	v_and_b32_e32 v157, 0xffff0000, v157
	v_and_b32_e32 v156, 0xffff0000, v156
	v_lshlrev_b32_e32 v169, 16, v153
	v_lshlrev_b32_e32 v168, 16, v152
	v_and_b32_e32 v171, 0xffff0000, v153
	v_and_b32_e32 v170, 0xffff0000, v152
	v_pk_mul_f32 v[152:153], v[156:157], v[156:157]
	v_lshlrev_b32_e32 v172, 16, v150
	v_pk_fma_f32 v[152:153], v[166:167], v[166:167], v[152:153]
	v_and_b32_e32 v173, 0xffff0000, v150
	v_lshlrev_b32_e32 v150, 16, v151
	v_lshlrev_b32_e32 v174, 16, v146
	v_pk_add_f32 v[152:153], v[152:153], v[152:153] op_sel_hi:[0,1]
	v_pk_mul_f32 v[176:177], v[170:171], v[170:171]
	v_and_b32_e32 v151, 0xffff0000, v151
	v_pk_fma_f32 v[176:177], v[168:169], v[168:169], v[176:177]
	v_mul_f32_e32 v175, v172, v172
	v_mul_f32_e32 v179, v173, v173
	v_mul_f32_e32 v152, v150, v150
	v_mov_b32_e32 v178, v174
	v_and_b32_e32 v165, 0xffff0000, v146
	v_lshlrev_b32_e32 v146, 16, v147
	v_and_b32_e32 v147, 0xffff0000, v147
	v_pk_add_f32 v[176:177], v[176:177], v[176:177] op_sel_hi:[0,1]
	v_pk_fma_f32 v[180:181], v[150:151], v[150:151], v[152:153] op_sel_hi:[1,1,0]
	v_pk_add_f32 v[178:179], v[174:175], v[178:179]
	v_mul_f32_e32 v180, v165, v165
	v_mul_f32_e32 v176, v146, v146
	v_mul_f32_e32 v152, v147, v147
	v_mul_f32_e32 v182, v174, v174
	v_mov_b32_e32 v183, v179
	v_pk_add_f32 v[178:179], v[182:183], v[180:181]
	v_pk_add_f32 v[152:153], v[176:177], v[152:153]
	v_mov_b32_e32 v184, v166
	v_pk_add_f32 v[152:153], v[178:179], v[152:153]
	v_mov_b32_e32 v185, v156
	v_add_f32_e32 v152, v152, v153
	s_waitcnt lgkmcnt(0)
	s_nop 1
	v_add_f32_dpp v152, v152, v152 quad_perm:[1,0,3,2] row_mask:0xf bank_mask:0xf
	s_nop 1
	v_add_f32_dpp v152, v152, v152 quad_perm:[2,3,0,1] row_mask:0xf bank_mask:0xf
	s_nop 1
	v_add_f32_dpp v152, v152, v152 row_half_mirror row_mask:0xf bank_mask:0xf
	s_nop 1
	v_add_f32_dpp v152, v152, v152 row_mirror row_mask:0xf bank_mask:0xf
	v_mov_b32_e32 v153, v152
	s_nop 1
	v_permlane16_swap_b32_e32 v152, v153
	v_add_f32_e32 v152, v152, v153
	v_mov_b32_e32 v153, v152
	s_nop 1
	v_permlane32_swap_b32_e32 v152, v153
	v_add_f32_e32 v152, v152, v153
	v_mov_b32_e32 v156, v167
	v_mov_b32_e32 v166, v168
	v_mov_b32_e32 v167, v170
	v_lshlrev_b32_e32 v176, 16, v154
	v_and_b32_e32 v177, 0xffff0000, v154
	v_lshlrev_b32_e32 v154, 16, v148
	v_and_b32_e32 v179, 0xffff0000, v144
	v_and_b32_e32 v181, 0xffff0000, v142
	v_mov_b32_e32 v153, v152
	v_lshlrev_b32_e32 v152, 16, v155
	v_mov_b32_e32 v170, v169
	s_mov_b32 s15, 0x6800000
	v_mov_b32_e32 v175, v153
	v_and_b32_e32 v153, 0xffff0000, v155
	v_and_b32_e32 v155, 0xffff0000, v148
	v_lshlrev_b32_e32 v148, 16, v149
	v_and_b32_e32 v149, 0xffff0000, v149
	v_lshlrev_b32_e32 v178, 16, v144
	v_lshlrev_b32_e32 v144, 16, v145
	v_and_b32_e32 v145, 0xffff0000, v145
	v_lshlrev_b32_e32 v180, 16, v142
	v_lshlrev_b32_e32 v142, 16, v143
	v_and_b32_e32 v143, 0xffff0000, v143
	v_fmamk_f32 v175, v175, 0x3a800000, v214
	v_rsq_f32_e32 v182, v175
	v_mov_b32_e32 v175, v165
	v_pk_mul_f32 v[166:167], v[182:183], v[166:167] op_sel_hi:[0,1]
	v_pk_mul_f32 v[184:185], v[182:183], v[184:185] op_sel_hi:[0,1]
	v_pk_mul_f32 v[156:157], v[182:183], v[156:157] op_sel_hi:[0,1]
	v_pk_fma_f32 v[154:155], v[6:7], v[166:167], v[154:155]
	v_pk_mul_f32 v[166:167], v[172:173], v[182:183] op_sel_hi:[1,0]
	v_pk_mul_f32 v[150:151], v[150:151], v[182:183] op_sel_hi:[1,0]
	v_pk_fma_f32 v[152:153], v[4:5], v[156:157], v[152:153]
	v_pk_fma_f32 v[156:157], v[2:3], v[184:185], v[176:177]
	v_pk_fma_f32 v[144:145], v[12:13], v[150:151], v[144:145]
	v_pk_fma_f32 v[150:151], v[10:11], v[166:167], v[178:179]
	v_pk_mul_f32 v[166:167], v[174:175], v[182:183] op_sel_hi:[1,0]
	v_pk_mul_f32 v[146:147], v[146:147], v[182:183] op_sel_hi:[1,0]
	v_pk_mul_f32 v[168:169], v[182:183], v[170:171] op_sel_hi:[0,1]
	v_pk_fma_f32 v[142:143], v[16:17], v[146:147], v[142:143]
	v_pk_fma_f32 v[146:147], v[14:15], v[166:167], v[180:181]
	v_mul_f32_e32 v165, v157, v157
	v_mul_f32_e32 v166, v153, v153
	v_pk_fma_f32 v[148:149], v[8:9], v[168:169], v[148:149]
	v_fmac_f32_e32 v165, v156, v156
	v_fmac_f32_e32 v166, v152, v152
	v_add_f32_e32 v165, v165, v166
	v_mul_f32_e32 v166, v155, v155
	v_mul_f32_e32 v167, v149, v149
	v_fmac_f32_e32 v166, v154, v154
	v_fmac_f32_e32 v167, v148, v148
	v_add_f32_e32 v166, v166, v167
	v_add_f32_e32 v165, v165, v166
	v_mul_f32_e32 v166, v151, v151
	v_mul_f32_e32 v167, v145, v145
	v_fmac_f32_e32 v166, v150, v150
	v_fmac_f32_e32 v167, v144, v144
	v_add_f32_e32 v166, v166, v167
	v_add_f32_e32 v165, v166, v165
	v_mul_f32_e32 v166, v147, v147
	v_mul_f32_e32 v167, v143, v143
	v_fmac_f32_e32 v166, v146, v146
	v_fmac_f32_e32 v167, v142, v142
	v_add_f32_e32 v166, v166, v167
	v_add_f32_e32 v165, v166, v165
	v_cvt_pk_bf16_f32 v168, v156, v157
	v_cvt_pk_bf16_f32 v169, v152, v153
	v_lshl_add_u64 v[166:167], s[28:29], 0, v[0:1]
	v_add_co_u32_e32 v166, vcc, s15, v166
	v_addc_co_u32_e32 v167, vcc, 0, v167, vcc
	global_store_dwordx2 v[166:167], v[168:169], off
	v_cvt_pk_bf16_f32 v168, v154, v155
	v_cvt_pk_bf16_f32 v169, v148, v149
	global_store_dwordx2 v[166:167], v[168:169], off offset:512
	v_cvt_pk_bf16_f32 v168, v150, v151
	v_cvt_pk_bf16_f32 v169, v144, v145
	s_waitcnt lgkmcnt(0)
	s_nop 1
	v_add_f32_dpp v165, v165, v165 quad_perm:[1,0,3,2] row_mask:0xf bank_mask:0xf
	s_nop 1
	v_add_f32_dpp v165, v165, v165 quad_perm:[2,3,0,1] row_mask:0xf bank_mask:0xf
	s_nop 1
	v_add_f32_dpp v165, v165, v165 row_half_mirror row_mask:0xf bank_mask:0xf
	s_nop 1
	v_add_f32_dpp v165, v165, v165 row_mirror row_mask:0xf bank_mask:0xf
	v_mov_b32_e32 v170, v165
	s_nop 1
	v_permlane16_swap_b32_e32 v165, v170
	v_add_f32_e32 v165, v165, v170
	v_mov_b32_e32 v170, v165
	s_nop 1
	v_permlane32_swap_b32_e32 v165, v170
	v_add_f32_e32 v165, v165, v170
	v_fmamk_f32 v165, v165, 0x3a800000, v214
	v_rsq_f32_e32 v165, v165
	global_store_dwordx2 v[166:167], v[168:169], off offset:1024
	v_cvt_pk_bf16_f32 v168, v146, v147
	v_cvt_pk_bf16_f32 v169, v142, v143
	global_store_dwordx2 v[166:167], v[168:169], off offset:1536
	s_and_saveexec_b64 s[30:31], s[4:5]
	s_cbranch_execz .LBB0_989
	global_store_dword v1, v165, s[22:23]

; __device__ __forceinline__ unsigned pk2(float lo, float hi) { const f32x2_pk v = {lo, hi}; return __builtin_bit_cast(unsigned, __builtin_convertvector(v, bf16x2_pk)); }
; __device__ __forceinline__ float bflo(unsigned w) { return __uint_as_float(w << 16); }
; __device__ __forceinline__ float bfhi(unsigned w) { return __uint_as_float(w & 0xffff0000u); }
; #define RS ((float*)(WSP() + WS_RS))
; template <bool HAS_G, bool HAS_PRE, bool HAS_F, bool HAS_P, bool HIN32, bool HOUT32> ...
;     ...
;         for (int j = 0; j < 4; ++j) { if (HIN32) v[j] = h32[u][j]; else v[j] = (f32x4){bflo(hbr[u][j].x), bfhi(hbr[u][j].x), bflo(hbr[u][j].y), bfhi(hbr[u][j].y)};
;             if (HAS_G) g[j] = (f32x4){bflo(gbr[u][j].x), bfhi(gbr[u][j].x), bflo(gbr[u][j].y), bfhi(gbr[u][j].y)}; }
;         if (m + 2 * NGW < M) E_LOAD(u, m + 2 * NGW);
;         if (HAS_G) {
;             float ss = 0.f;
; #pragma unroll
;             for (int j = 0; j < 4; ++j) ss += (g[j][0] * g[j][0] + g[j][1] * g[j][1]) + (g[j][2] * g[j][2] + g[j][3] * g[j][3]);
;             const float r = __builtin_amdgcn_rsqf(wave_sum(ss) * (1.f / DM) + EPS)    ;
; #pragma unroll
;             for (int j = 0; j < 4; ++j) { v[j] = v[j] + g[j] * r * gp[j];
;                 if (HOUT32) __builtin_nontemporal_store(v[j], (f32x4*)((float*)hout_ + mm * DM + 4 * lane + 256 * j));
;                 else { v2u w; w.x = pk2(v[j][0], v[j][1]); w.y = pk2(v[j][2], v[j][3]); *(v2u*)((bf16*)hout_ + mm * DM + 4 * lane + 256 * j) = w; } }
;         }
;         if (!HAS_G && hout_) {
; #pragma unroll
;             for (int j = 0; j < 4; ++j) { v2u w; w.x = pk2(v[j][0], v[j][1]); w.y = pk2(v[j][2], v[j][3]); *(v2u*)((bf16*)hout_ + mm * DM + 4 * lane + 256 * j) = w; } }
;         if (HAS_PRE) {
;             float ss = 0.f;
; #pragma unroll
;             for (int j = 0; j < 4; ++j) ss += (v[j][0] * v[j][0] + v[j][1] * v[j][1]) + (v[j][2] * v[j][2] + v[j][3] * v[j][3]);
;             const float r = __builtin_amdgcn_rsqf(wave_sum(ss) * (1.f / DM) + EPS)    ;
;             if (lane == 0) RS[mm] = r;
.LBB0_993:
	v_lshlrev_b32_e32 v167, 16, v141
	v_lshlrev_b32_e32 v166, 16, v140
	v_and_b32_e32 v141, 0xffff0000, v141
	v_and_b32_e32 v140, 0xffff0000, v140
	v_lshlrev_b32_e32 v174, 16, v134
	v_and_b32_e32 v165, 0xffff0000, v134
	v_lshlrev_b32_e32 v176, 16, v135
	v_and_b32_e32 v177, 0xffff0000, v135
	v_pk_mul_f32 v[134:135], v[140:141], v[140:141]
	v_lshlrev_b32_e32 v169, 16, v139
	v_lshlrev_b32_e32 v168, 16, v138
	v_and_b32_e32 v139, 0xffff0000, v139
	v_and_b32_e32 v138, 0xffff0000, v138
	v_pk_fma_f32 v[134:135], v[166:167], v[166:167], v[134:135]
	v_lshlrev_b32_e32 v170, 16, v136
	v_and_b32_e32 v171, 0xffff0000, v136
	v_lshlrev_b32_e32 v172, 16, v137
	v_and_b32_e32 v173, 0xffff0000, v137
	v_pk_add_f32 v[134:135], v[134:135], v[134:135] op_sel_hi:[0,1]
	v_pk_mul_f32 v[136:137], v[138:139], v[138:139]
	v_mul_f32_e32 v175, v170, v170
	v_pk_fma_f32 v[136:137], v[168:169], v[168:169], v[136:137]
	v_mul_f32_e32 v179, v171, v171
	v_mul_f32_e32 v134, v172, v172
	v_mov_b32_e32 v178, v174
	v_pk_add_f32 v[136:137], v[136:137], v[136:137] op_sel_hi:[0,1]
	v_pk_fma_f32 v[180:181], v[172:173], v[172:173], v[134:135] op_sel_hi:[1,1,0]
	v_pk_add_f32 v[178:179], v[174:175], v[178:179]
	v_mul_f32_e32 v180, v165, v165
	v_mul_f32_e32 v136, v176, v176
	v_mul_f32_e32 v134, v177, v177
	v_mul_f32_e32 v182, v174, v174
	v_mov_b32_e32 v183, v179
	v_pk_add_f32 v[178:179], v[182:183], v[180:181]
	v_pk_add_f32 v[134:135], v[136:137], v[134:135]
	v_lshlrev_b32_e32 v182, 16, v126
	v_pk_add_f32 v[134:135], v[178:179], v[134:135]
	v_and_b32_e32 v183, 0xffff0000, v126
	v_add_f32_e32 v134, v134, v135
	s_waitcnt lgkmcnt(0)
	s_nop 1
	v_add_f32_dpp v134, v134, v134 quad_perm:[1,0,3,2] row_mask:0xf bank_mask:0xf
	s_nop 1
	v_add_f32_dpp v134, v134, v134 quad_perm:[2,3,0,1] row_mask:0xf bank_mask:0xf
	s_nop 1
	v_add_f32_dpp v134, v134, v134 row_half_mirror row_mask:0xf bank_mask:0xf
	s_nop 1
	v_add_f32_dpp v134, v134, v134 row_mirror row_mask:0xf bank_mask:0xf
	v_mov_b32_e32 v135, v134
	s_nop 1
	v_permlane16_swap_b32_e32 v134, v135
	v_add_f32_e32 v134, v134, v135
	v_mov_b32_e32 v135, v134
	s_nop 1
	v_permlane32_swap_b32_e32 v134, v135
	v_add_f32_e32 v134, v134, v135
	v_lshlrev_b32_e32 v126, 16, v127
	v_and_b32_e32 v127, 0xffff0000, v127
	v_lshlrev_b32_e32 v178, 16, v130
	v_and_b32_e32 v179, 0xffff0000, v130
	v_lshlrev_b32_e32 v130, 16, v131
	v_and_b32_e32 v131, 0xffff0000, v131
	v_mov_b32_e32 v175, v165
	v_lshlrev_b32_e32 v180, 16, v128
	v_mov_b32_e32 v136, v134
	v_lshlrev_b32_e32 v134, 16, v132
	v_and_b32_e32 v135, 0xffff0000, v132
	v_lshlrev_b32_e32 v132, 16, v133
	v_and_b32_e32 v133, 0xffff0000, v133
	v_and_b32_e32 v181, 0xffff0000, v128
	v_lshlrev_b32_e32 v128, 16, v129
	v_and_b32_e32 v129, 0xffff0000, v129
	s_add_i32 s30, s70, s13
	s_ashr_i32 s31, s30, 31
	s_lshl_b64 s[34:35], s[30:31], 11
	v_fmamk_f32 v136, v136, 0x3a800000, v214
	v_rsq_f32_e32 v184, v136
	v_mov_b32_e32 v136, v166
	v_mov_b32_e32 v137, v140
	v_mov_b32_e32 v140, v167
	v_pk_mul_f32 v[186:187], v[184:185], v[136:137] op_sel_hi:[0,1]
	v_pk_mul_f32 v[136:137], v[184:185], v[140:141] op_sel_hi:[0,1]
	v_pk_fma_f32 v[136:137], v[4:5], v[136:137], v[132:133]
	v_pk_fma_f32 v[140:141], v[2:3], v[186:187], v[134:135]
	v_mov_b32_e32 v132, v168
	v_mov_b32_e32 v133, v138
	v_mov_b32_e32 v138, v169
	v_pk_mul_f32 v[166:167], v[176:177], v[184:185] op_sel_hi:[1,0]
	v_pk_mul_f32 v[134:135], v[184:185], v[132:133] op_sel_hi:[0,1]
	v_pk_mul_f32 v[132:133], v[184:185], v[138:139] op_sel_hi:[0,1]
	v_pk_fma_f32 v[126:127], v[16:17], v[166:167], v[126:127]
	v_mul_f32_e32 v165, v141, v141
	v_mul_f32_e32 v166, v137, v137
	v_pk_fma_f32 v[132:133], v[8:9], v[132:133], v[130:131]
	v_pk_fma_f32 v[138:139], v[6:7], v[134:135], v[178:179]
	v_fmac_f32_e32 v165, v140, v140
	v_fmac_f32_e32 v166, v136, v136
	v_add_f32_e32 v165, v165, v166
	v_mul_f32_e32 v166, v139, v139
	v_mul_f32_e32 v167, v133, v133
	v_pk_mul_f32 v[130:131], v[170:171], v[184:185] op_sel_hi:[1,0]
	v_pk_mul_f32 v[134:135], v[172:173], v[184:185] op_sel_hi:[1,0]
	v_fmac_f32_e32 v166, v138, v138
	v_fmac_f32_e32 v167, v132, v132
	v_pk_fma_f32 v[128:129], v[12:13], v[134:135], v[128:129]
	v_pk_fma_f32 v[134:135], v[10:11], v[130:131], v[180:181]
	v_add_f32_e32 v166, v166, v167
	v_add_f32_e32 v165, v165, v166
	v_mul_f32_e32 v166, v135, v135
	v_mul_f32_e32 v167, v129, v129
	v_pk_mul_f32 v[130:131], v[174:175], v[184:185] op_sel_hi:[1,0]
	v_fmac_f32_e32 v166, v134, v134
	v_fmac_f32_e32 v167, v128, v128
	v_pk_fma_f32 v[130:131], v[14:15], v[130:131], v[182:183]
	v_add_f32_e32 v166, v166, v167
	v_add_f32_e32 v165, v166, v165
	v_mul_f32_e32 v166, v131, v131
	v_mul_f32_e32 v167, v127, v127
	v_fmac_f32_e32 v166, v130, v130
	v_fmac_f32_e32 v167, v126, v126
	v_add_f32_e32 v166, v166, v167
	v_add_f32_e32 v165, v166, v165
	v_cvt_pk_bf16_f32 v168, v140, v141
	v_lshl_add_u64 v[166:167], v[98:99], 0, s[34:35]
	v_cvt_pk_bf16_f32 v169, v136, v137
	global_store_dwordx2 v[166:167], v[168:169], off
	v_cvt_pk_bf16_f32 v168, v138, v139
	v_cvt_pk_bf16_f32 v169, v132, v133
	global_store_dwordx2 v[166:167], v[168:169], off offset:512
	v_cvt_pk_bf16_f32 v168, v134, v135
	v_cvt_pk_bf16_f32 v169, v128, v129
	global_store_dwordx2 v[166:167], v[168:169], off offset:1024
	s_waitcnt lgkmcnt(0)
	s_nop 1
	v_add_f32_dpp v165, v165, v165 quad_perm:[1,0,3,2] row_mask:0xf bank_mask:0xf
	s_nop 1
	v_add_f32_dpp v165, v165, v165 quad_perm:[2,3,0,1] row_mask:0xf bank_mask:0xf
	s_nop 1
	v_add_f32_dpp v165, v165, v165 row_half_mirror row_mask:0xf bank_mask:0xf
	s_nop 1
	v_add_f32_dpp v165, v165, v165 row_mirror row_mask:0xf bank_mask:0xf
	v_mov_b32_e32 v170, v165
	s_nop 1
	v_permlane16_swap_b32_e32 v165, v170
	v_add_f32_e32 v165, v165, v170
	v_mov_b32_e32 v170, v165
	s_nop 1
	v_permlane32_swap_b32_e32 v165, v170
	v_add_f32_e32 v165, v165, v170
	v_fmamk_f32 v165, v165, 0x3a800000, v214
	v_rsq_f32_e32 v165, v165
	v_cvt_pk_bf16_f32 v168, v130, v131
	v_cvt_pk_bf16_f32 v169, v126, v127
	global_store_dwordx2 v[166:167], v[168:169], off offset:1536
	s_and_saveexec_b64 s[34:35], s[4:5]
	s_cbranch_execz .LBB0_995
	s_lshl_b64 s[62:63], s[30:31], 2
	s_add_u32 s62, s48, s62
	s_addc_u32 s63, s49, s63
	global_store_dword v1, v165, s[62:63]
